# grid barrier: non-leader workgroups poll the global release generation directly, per-XCD release atomic removed
# speedup vs baseline: 1.0054x; 1.0054x over previous
; __device__ __forceinline__ unsigned xb_ld(unsigned* p)              { return __hip_atomic_load(p, __ATOMIC_RELAXED, __HIP_MEMORY_SCOPE_AGENT); }
; __device__ __forceinline__ unsigned xb_add(unsigned* p, unsigned v) { return __hip_atomic_fetch_add(p, v, __ATOMIC_RELAXED, __HIP_MEMORY_SCOPE_AGENT); }
; #define XB_SPIN(cond, bar) do { unsigned _sp = 0; while (cond) { __builtin_amdgcn_s_sleep(1); \
;     if ((++_sp & 255u) == 0u) { if (xb_ld(&(bar)[XB_TMO])) break; if (_sp > XB_SPIN_CAP) { atomicAdd(&(bar)[XB_TMO], 1u); break; } } } } while (0)
; __device__ __forceinline__ void xcd_barrier(const XcdBarrier& b) {
;     ...
;         const unsigned old = xb_add(&bar[XB_XSUB(b.x)], 1u);
;         const unsigned gen = old / nloc;
;         if (old + 1u == (gen + 1u) * nloc) {
;             __builtin_amdgcn_fence(__ATOMIC_RELEASE, "agent");
;             asm volatile("s_waitcnt vmcnt(0)" ::: "memory");
;             const unsigned og = xb_add(&bar[XB_TOP], 1u);
;             const unsigned tg = og / nx;
;             if (og + 1u == (tg + 1u) * nx) xb_add(&bar[XB_TOPGEN], 1u);
;             else XB_SPIN(xb_ld(&bar[XB_TOPGEN]) == tg, bar);
;             __builtin_amdgcn_fence(__ATOMIC_ACQUIRE, "agent");
;             xb_add(&bar[XB_XGEN(b.x)], 1u);
;             asm volatile("s_waitcnt vmcnt(0)" ::: "memory");
;         } else {
;             XB_SPIN(xb_ld(&bar[XB_XGEN(b.x)]) == gen, bar);
.LBB0_693:
	v_readlane_b32 s4, v254, 47
	v_readlane_b32 s5, v254, 48
	v_cvt_f32_u32_e32 v1, v2
	v_sub_u32_e32 v5, 0, v2
	v_rcp_iflag_f32_e32 v1, v1
	s_nop 1
	global_atomic_add v4, v3, v213, s[4:5] sc0
	v_mul_f32_e32 v1, 0x4f7ffffe, v1
	v_cvt_u32_f32_e32 v1, v1
	v_mul_lo_u32 v5, v5, v1
	v_mul_hi_u32 v5, v1, v5
	v_add_u32_e32 v1, v1, v5
	s_waitcnt vmcnt(0)
	v_mul_hi_u32 v1, v4, v1
	v_mul_lo_u32 v5, v1, v2
	v_sub_u32_e32 v5, v4, v5
	v_add_u32_e32 v6, 1, v1
	v_cmp_ge_u32_e32 vcc, v5, v2
	v_add_u32_e32 v4, 1, v4
	s_nop 0
	v_cndmask_b32_e32 v1, v1, v6, vcc
	v_sub_u32_e32 v6, v5, v2
	v_cndmask_b32_e32 v5, v5, v6, vcc
	v_add_u32_e32 v6, 1, v1
	v_cmp_ge_u32_e32 vcc, v5, v2
	s_nop 1
	v_cndmask_b32_e32 v1, v1, v6, vcc
	v_mul_lo_u32 v5, v2, v1
	v_add_u32_e32 v2, v5, v2
	v_cmp_ne_u32_e32 vcc, v4, v2
	s_and_saveexec_b64 s[4:5], vcc
	s_xor_b64 s[22:23], exec, s[4:5]
	s_cbranch_execz .LBB0_707
	v_readlane_b32 s4, v254, 53
	v_readlane_b32 s5, v254, 54
	s_waitcnt lgkmcnt(0)
	s_nop 3
	global_load_dword v0, v3, s[4:5] sc1
	s_waitcnt vmcnt(0)
	v_cmp_eq_u32_e32 vcc, v0, v1
	s_and_saveexec_b64 s[24:25], vcc
	s_cbranch_execz .LBB0_706
	s_mov_b32 s4, 1
	s_mov_b64 s[26:27], 0
	s_branch .LBB0_697

; __device__ __forceinline__ unsigned xb_ld(unsigned* p)              { return __hip_atomic_load(p, __ATOMIC_RELAXED, __HIP_MEMORY_SCOPE_AGENT); }
; #define XB_SPIN(cond, bar) do { unsigned _sp = 0; while (cond) { __builtin_amdgcn_s_sleep(1); \
;     if ((++_sp & 255u) == 0u) { if (xb_ld(&(bar)[XB_TMO])) break; if (_sp > XB_SPIN_CAP) { atomicAdd(&(bar)[XB_TMO], 1u); break; } } } } while (0)
; __device__ __forceinline__ void xcd_barrier(const XcdBarrier& b) {
;     ...
;             XB_SPIN(xb_ld(&bar[XB_XGEN(b.x)]) == gen, bar);
.LBB0_701:
	v_readlane_b32 s18, v254, 53
	v_readlane_b32 s19, v254, 54
	s_add_i32 s4, s4, 1
	s_mov_b64 s[38:39], -1
	s_nop 2
	global_load_dword v0, v3, s[18:19] sc1
	s_waitcnt vmcnt(0)
	v_cmp_ne_u32_e32 vcc, v0, v1
	s_orn2_b64 s[36:37], vcc, exec
	s_branch .LBB0_696

; __device__ __forceinline__ unsigned xb_ld(unsigned* p)              { return __hip_atomic_load(p, __ATOMIC_RELAXED, __HIP_MEMORY_SCOPE_AGENT); }
; __device__ __forceinline__ unsigned xb_add(unsigned* p, unsigned v) { return __hip_atomic_fetch_add(p, v, __ATOMIC_RELAXED, __HIP_MEMORY_SCOPE_AGENT); }
; #define XB_SPIN(cond, bar) do { unsigned _sp = 0; while (cond) { __builtin_amdgcn_s_sleep(1); \
;     if ((++_sp & 255u) == 0u) { if (xb_ld(&(bar)[XB_TMO])) break; if (_sp > XB_SPIN_CAP) { atomicAdd(&(bar)[XB_TMO], 1u); break; } } } } while (0)
; __device__ __forceinline__ void xcd_barrier(const XcdBarrier& b) {
;     ...
;             else XB_SPIN(xb_ld(&bar[XB_TOPGEN]) == tg, bar);
;             __builtin_amdgcn_fence(__ATOMIC_ACQUIRE, "agent");
;             xb_add(&bar[XB_XGEN(b.x)], 1u);
;             asm volatile("s_waitcnt vmcnt(0)" ::: "memory");
.LBB0_728:
	s_or_b64 exec, exec, s[22:23]
	v_readlane_b32 s4, v254, 49
	v_readlane_b32 s5, v254, 50
	s_waitcnt vmcnt(0)
	buffer_inv sc1
	s_nop 2
	s_waitcnt vmcnt(0)
